# NSA selected loop: leading K-fragment LDS reads issued directly after the barrier (before next-tile loads and the selection test); skip path drains them
# baseline (speedup 1.0000x reference)
.LBB0_1651:
	s_waitcnt lgkmcnt(0)
	s_add_i32 s80, s80, 1
	s_mov_b64 s[66:67], 0x58000
	s_cmp_lg_u32 s79, s80
	v_lshl_add_u64 v[14:15], v[14:15], 0, s[66:67]
	s_cbranch_scc0 .LBB0_1660
.LBB0_1652:
	s_bitcmp1_b32 s80, 0
	s_cselect_b32 s66, 0x2400, 0
	s_add_i32 s81, s66, 0
	v_add3_u32 v10, s81, v125, v0
	s_cmp_ge_i32 s80, s76
	s_waitcnt vmcnt(0)
	ds_write_b128 v10, v[2:5]
	ds_write_b128 v10, v[6:9] offset:18432
	s_waitcnt lgkmcnt(0)
	s_barrier
	v_add3_u32 v112, s81, v126, v127
	ds_read_b128 v[10:13], v112
	ds_read_b128 v[220:223], v112 offset:4608
	ds_read_b128 v[240:243], v112 offset:32
	ds_read_b128 v[244:247], v112 offset:4640
	ds_read_b128 v[248:251], v112 offset:64
	s_cbranch_scc1 .LBB0_1654
	global_load_dwordx4 v[2:5], v[14:15], off offset:-128
	global_load_dwordx4 v[6:9], v[14:15], off
.LBB0_1654:
	s_lshr_b32 s66, s80, 5
	v_mov_b32_e32 v252, v224
	s_cmp_eq_u32 s66, 0
	s_cbranch_scc1 .Lbm_done
	v_mov_b32_e32 v252, v225
	s_cmp_eq_u32 s66, 1
	s_cbranch_scc1 .Lbm_done
	v_mov_b32_e32 v252, v231
	s_cmp_eq_u32 s66, 2
	s_cbranch_scc1 .Lbm_done
	v_mov_b32_e32 v252, v237
.Lbm_done:
	s_and_b32 s66, s80, 31
	v_lshrrev_b32_e32 v253, s80, v252
	v_bfe_u32 v252, v252, s66, 1
	v_and_b32_e32 v253, 1, v253
	v_cmp_ne_u32_e32 vcc, 0, v252
	v_cmp_eq_u32_e64 s[66:67], 1, v253
	s_cbranch_vccz .LBB0_1651
	v_cndmask_b32_e64 v80, v236, -v130, s[66:67]
	v_mov_b32_e32 v81, v80
	v_mov_b32_e32 v82, v80
	v_mov_b32_e32 v83, v80
	v_mov_b32_e32 v84, v80
	v_mov_b32_e32 v85, v80
	v_mov_b32_e32 v86, v80
	v_mov_b32_e32 v87, v80
	v_mov_b32_e32 v88, v80
	v_mov_b32_e32 v89, v80
	v_mov_b32_e32 v90, v80
	v_mov_b32_e32 v91, v80
	v_mov_b32_e32 v92, v80
	v_mov_b32_e32 v93, v80
	v_mov_b32_e32 v94, v80
	v_mov_b32_e32 v95, v80
	s_cmp_lg_u32 s76, s80
	s_waitcnt lgkmcnt(4)
	v_mfma_f32_32x32x16_bf16 v[96:111], v[10:13], v[144:147], v[80:95]
	ds_read_b128 v[10:13], v112 offset:4672
	s_waitcnt lgkmcnt(4)
	v_mfma_f32_32x32x16_bf16 v[80:95], v[220:223], v[144:147], v[80:95]
	ds_read_b128 v[220:223], v112 offset:96
	s_waitcnt lgkmcnt(4)
	v_mfma_f32_32x32x16_bf16 v[96:111], v[240:243], v[148:151], v[96:111]
	ds_read_b128 v[240:243], v112 offset:4704
	s_waitcnt lgkmcnt(4)
	v_mfma_f32_32x32x16_bf16 v[80:95], v[244:247], v[148:151], v[80:95]
	s_waitcnt lgkmcnt(3)
	v_mfma_f32_32x32x16_bf16 v[96:111], v[248:251], v[152:155], v[96:111]
	s_waitcnt lgkmcnt(2)
	v_mfma_f32_32x32x16_bf16 v[80:95], v[10:13], v[152:155], v[80:95]
	s_waitcnt lgkmcnt(1)
	v_mfma_f32_32x32x16_bf16 v[96:111], v[220:223], v[156:159], v[96:111]
	s_waitcnt lgkmcnt(0)
	v_mfma_f32_32x32x16_bf16 v[80:95], v[240:243], v[156:159], v[80:95]
	s_cbranch_scc1 .LBB0_1657
	s_nop 7
	v_cndmask_b32_e64 v10, v96, v236, s[0:1]
	s_nop 1
	v_cndmask_b32_e64 v80, v80, v236, s[2:3]
	v_cndmask_b32_e64 v97, v236, v97, s[4:5]
	v_cndmask_b32_e64 v96, v10, v96, s[4:5]
	v_cndmask_b32_e64 v81, v81, v236, s[6:7]
	v_cndmask_b32_e64 v98, v98, v236, s[8:9]
	v_cndmask_b32_e64 v82, v82, v236, s[10:11]
	v_cndmask_b32_e64 v99, v99, v236, s[12:13]
	v_cndmask_b32_e64 v83, v83, v236, s[14:15]
	v_cndmask_b32_e64 v100, v100, v236, s[16:17]
	v_cndmask_b32_e64 v84, v84, v236, s[18:19]
	v_cndmask_b32_e64 v101, v101, v236, s[20:21]
	v_cndmask_b32_e64 v85, v85, v236, s[22:23]
	v_cndmask_b32_e64 v102, v102, v236, s[24:25]
	v_cndmask_b32_e64 v86, v86, v236, s[26:27]
	v_cndmask_b32_e64 v103, v103, v236, s[28:29]
	v_cndmask_b32_e64 v87, v87, v236, s[30:31]
	v_cndmask_b32_e64 v104, v104, v236, s[34:35]
	v_cndmask_b32_e64 v88, v88, v236, s[36:37]
	v_cndmask_b32_e64 v105, v105, v236, s[38:39]
	v_cndmask_b32_e64 v89, v89, v236, s[40:41]
	v_cndmask_b32_e64 v106, v106, v236, s[42:43]
	v_cndmask_b32_e64 v90, v90, v236, s[44:45]
	v_cndmask_b32_e64 v107, v107, v236, s[46:47]
	v_cndmask_b32_e64 v91, v91, v236, s[48:49]
	v_cndmask_b32_e64 v108, v108, v236, s[50:51]
	v_cndmask_b32_e64 v92, v92, v236, s[52:53]
	v_cndmask_b32_e64 v109, v109, v236, s[54:55]
	v_cndmask_b32_e64 v93, v93, v236, s[56:57]
	v_cndmask_b32_e64 v110, v110, v236, s[58:59]
	v_cndmask_b32_e64 v94, v94, v236, s[60:61]
	v_cndmask_b32_e64 v111, v111, v236, s[62:63]
	v_cndmask_b32_e64 v95, v95, v236, s[64:65]
